# phase 0 keeps 976 items (diff-V cache conversion moved to the first swiglu tail) and its last partial round skips the 48 workgroups that carry two mod-vector items
# baseline (speedup 1.0000x reference)
.LBB0_527:
	v_readlane_b32 s80, v255, 42
	v_readlane_b32 s84, v255, 44
	v_readlane_b32 s81, v255, 43
	v_readlane_b32 s85, v255, 45
	v_readlane_b32 s77, v255, 46
	v_readlane_b32 s76, v255, 47
	s_barrier
	s_cmpk_lg_u32 s54, 0x100
	s_cbranch_scc1 .Lp0t_end_q1
	v_readlane_b32 s0, v255, 48
	s_cmp_eq_u32 s0, 2
	s_cbranch_scc0 .Lp0t_n0_q1
	s_cmp_lt_u32 s34, 64
	s_cbranch_scc1 .Lp0t_n0_q1
	s_sub_i32 s45, s34, 64
	s_add_i32 s45, s45, 0x450
	s_mov_b32 s68, 0xc0
	s_mov_b32 s69, 0x9df
	s_mov_b32 s58, 0x660
	s_mov_b32 s59, 0x5a0
	s_mov_b32 s61, 0x6e0
	s_mov_b32 s74, 0x40
	s_mov_b32 s78, 0x8e0
	s_mov_b32 s79, 0x100
	s_mov_b32 s70, 0x0
	s_mov_b32 s71, 0x0
	s_cmp_gt_i32 s45, s69
	s_cbranch_scc1 .Lp0t_n0_q1
	s_branch .Lp0_full

.LBB0_556:
	s_and_b64 vcc, exec, s[0:1]
	s_cbranch_vccz .LBB0_622
	s_mov_b32 s45, s34
	s_mov_b32 s68, s54
	s_mov_b32 s69, 0x3ff
	s_mov_b32 s58, 0x120
	s_mov_b32 s59, 0x120
	s_mov_b32 s61, 0x330
	s_mov_b32 s74, 0xffffffd0
	s_mov_b32 s78, 0x360
	s_mov_b32 s79, 0x630
	s_mov_b32 s70, 0x300
	s_mov_b32 s71, 0x330
	s_cmpk_eq_u32 s54, 0x100
	s_cbranch_scc1 .Lp0_full
	s_mov_b32 s45, s34
	s_mov_b32 s68, s54
	s_mov_b32 s69, 0x10bf
	s_mov_b32 s58, 0x7fffffff
	s_mov_b32 s59, 0x0
	s_mov_b32 s61, 0x7fffffff
	s_mov_b32 s74, 0x0
	s_mov_b32 s78, 0x7fffffff
	s_mov_b32 s79, 0x0
	s_mov_b32 s70, 0x0
	s_mov_b32 s71, 0x0
